# mode 1 GEMM rewritten by hand (same 128x128 tiles / task order): next tile prefetched before the epilogue, bf16 stores widened to 16 B per lane with v_permlane16_swap
# speedup vs baseline: 1.0564x; 1.0198x over previous
.LBB0_673:
	s_andn2_b64 vcc, exec, s[0:1]
	s_cbranch_vccnz .LBB0_709
	v_readlane_b32 s0, v239, 54
	s_cmp_lg_u32 s0, 0
	s_cbranch_scc1 .LBB0_709
	v_and_b32_e32 v137, 63, v144
	v_lshrrev_b32_e32 v138, 6, v144
	v_lshlrev_b32_e32 v0, 10, v138
	s_nop 0
	v_readfirstlane_b32 s38, v0
	v_lshrrev_b32_e32 v139, 3, v137
	v_lshl_add_u32 v139, v138, 3, v139
	v_lshrrev_b32_e32 v140, 1, v139
	v_xor_b32_e32 v140, v140, v137
	v_and_b32_e32 v140, 7, v140
	v_lshlrev_b32_e32 v140, 4, v140
	v_add_u32_e32 v141, 0, v139
	v_lshl_add_u32 v114, v141, 11, v140
	v_add_u32_e32 v141, 32, v139
	v_lshl_add_u32 v115, v141, 11, v140
	v_add_u32_e32 v141, 64, v139
	v_lshl_add_u32 v116, v141, 11, v140
	v_add_u32_e32 v141, 96, v139
	v_lshl_add_u32 v117, v141, 11, v140
	v_add_u32_e32 v141, 128, v139
	v_lshl_add_u32 v118, v141, 11, v140
	v_and_b32_e32 v142, 15, v137
	v_lshrrev_b32_e32 v143, 4, v137
	v_lshrrev_b32_e32 v204, 1, v138
	v_and_b32_e32 v205, 1, v138
	v_bfe_u32 v208, v137, 1, 3
	v_add_u32_e32 v206, 0, v143
	v_xor_b32_e32 v206, v206, v208
	v_lshlrev_b32_e32 v206, 4, v206
	v_lshl_add_u32 v127, v142, 7, v206
	v_lshl_add_u32 v119, v204, 13, v127
	v_lshl_add_u32 v121, v205, 13, v127
	v_add_u32_e32 v121, 0x4000, v121
	v_add_u32_e32 v127, 0x8000, v127
	v_add_u32_e32 v206, 4, v143
	v_xor_b32_e32 v206, v206, v208
	v_lshlrev_b32_e32 v206, 4, v206
	v_lshl_add_u32 v128, v142, 7, v206
	v_lshl_add_u32 v120, v204, 13, v128
	v_lshl_add_u32 v126, v205, 13, v128
	v_add_u32_e32 v126, 0x4000, v126
	v_add_u32_e32 v128, 0x8000, v128
	v_lshl_add_u32 v207, v204, 6, v142
	v_lshlrev_b32_e32 v141, 3, v143
	v_lshl_add_u32 v141, v205, 7, v141
	v_add_u32_e32 v0, 0, v207
	v_lshl_add_u32 v129, v0, 13, v141
	v_lshlrev_b32_e32 v133, 6, v0
	v_lshl_add_u32 v133, v143, 4, v133
	v_add_u32_e32 v0, 16, v207
	v_lshl_add_u32 v130, v0, 13, v141
	v_lshlrev_b32_e32 v134, 6, v0
	v_lshl_add_u32 v134, v143, 4, v134
	v_add_u32_e32 v0, 32, v207
	v_lshl_add_u32 v131, v0, 13, v141
	v_lshlrev_b32_e32 v135, 6, v0
	v_lshl_add_u32 v135, v143, 4, v135
	v_add_u32_e32 v0, 48, v207
	v_lshl_add_u32 v132, v0, 13, v141
	v_lshlrev_b32_e32 v136, 6, v0
	v_lshl_add_u32 v136, v143, 4, v136
	v_and_b32_e32 v141, 1, v143
	v_lshlrev_b32_e32 v141, 5, v141
	v_lshrrev_b32_e32 v208, 1, v143
	v_lshl_add_u32 v141, v208, 4, v141
	v_lshl_add_u32 v141, v205, 7, v141
	v_add_u32_e32 v0, 0, v207
	v_lshl_add_u32 v209, v0, 13, v141
	v_add_u32_e32 v0, 16, v207
	v_lshl_add_u32 v210, v0, 13, v141
	v_add_u32_e32 v0, 32, v207
	v_lshl_add_u32 v211, v0, 13, v141
	v_add_u32_e32 v0, 48, v207
	v_lshl_add_u32 v212, v0, 13, v141
	v_cmp_gt_u32_e32 vcc, 2, v143
	s_nop 3
	s_mov_b64 s[40:41], vcc
	s_andn2_b64 s[42:43], exec, vcc
	s_bfe_u32 s44, s38, 0x1000a
	s_mov_b32 s0, s91
	s_cmpk_ge_u32 s0, 0xff0
	s_cbranch_scc1 .Lq1_done
	s_mul_hi_u32 s1, s0, 0x88888889
	s_lshr_b32 s1, s1, 4
	s_mul_i32 s2, s1, 30
	s_sub_u32 s2, s0, s2
	s_cmp_eq_u32 s2, 29
	s_cselect_b32 s14, 1, 0
	s_lshl_b32 s15, s1, 18
	s_add_u32 s15, s15, 0x1a40000
	s_add_u32 s4, s26, s15
	s_addc_u32 s5, s27, 0
	s_lshl_b32 s15, s2, 18
	s_add_u32 s6, s26, s15
	s_addc_u32 s7, s27, 0
	s_barrier
	s_add_i32 m0, s38, 0x0
	s_nop 0
	global_load_lds_dwordx4 v114, s[4:5]
	s_add_i32 m0, s38, 0x4000
	s_nop 0
	global_load_lds_dwordx4 v114, s[6:7]
	s_add_i32 m0, s38, 0x1000
	s_nop 0
	global_load_lds_dwordx4 v115, s[4:5]
	s_add_i32 m0, s38, 0x5000
	s_nop 0
	global_load_lds_dwordx4 v115, s[6:7]
	s_add_i32 m0, s38, 0x2000
	s_nop 0
	global_load_lds_dwordx4 v116, s[4:5]
	s_add_i32 m0, s38, 0x6000
	s_nop 0
	global_load_lds_dwordx4 v116, s[6:7]
	s_add_i32 m0, s38, 0x3000
	s_nop 0
	global_load_lds_dwordx4 v117, s[4:5]
	s_add_i32 m0, s38, 0x7000
	s_nop 0
	global_load_lds_dwordx4 v117, s[6:7]
	s_cmp_eq_u32 s14, 1
	s_cbranch_scc0 .Lq1_nx0
	s_cmpk_lt_u32 s38, 0x800
	s_cbranch_scc0 .Lq1_nx0
	s_add_i32 m0, s38, 0x8000
	s_nop 0
	global_load_lds_dwordx4 v118, s[6:7]
.Lq1_nx0:
	s_add_u32 s4, s4, 0x80
	s_addc_u32 s5, s5, 0
	s_add_u32 s6, s6, 0x80
	s_addc_u32 s7, s7, 0
	s_waitcnt vmcnt(0)
.Lq1_task:
	s_mul_hi_u32 s1, s0, 0x88888889
	s_lshr_b32 s1, s1, 4
	s_mul_i32 s2, s1, 30
	s_sub_u32 s2, s0, s2
	s_cmp_eq_u32 s2, 29
	s_cselect_b32 s13, 1, 0
	s_mov_b32 s12, s2
	s_lshl_b32 s15, s1, 20
	s_lshl_b32 s45, s2, 8
	s_add_u32 s15, s15, s45
	s_add_u32 s15, s15, 0x3c40000
	s_add_u32 s8, s26, s15
	s_addc_u32 s9, s27, 0
	s_lshl_b32 s15, s1, 13
	s_add_u32 s15, s15, 0xf740000
	s_add_u32 s10, s26, s15
	s_addc_u32 s11, s27, 0
	v_mov_b32_e32 v2, 0
	v_mov_b32_e32 v3, 0
	v_mov_b32_e32 v4, 0
	v_mov_b32_e32 v5, 0
	v_mov_b32_e32 v6, 0
	v_mov_b32_e32 v7, 0
	v_mov_b32_e32 v8, 0
	v_mov_b32_e32 v9, 0
	v_mov_b32_e32 v10, 0
	v_mov_b32_e32 v11, 0
	v_mov_b32_e32 v12, 0
	v_mov_b32_e32 v13, 0
	v_mov_b32_e32 v14, 0
	v_mov_b32_e32 v15, 0
	v_mov_b32_e32 v16, 0
	v_mov_b32_e32 v17, 0
	v_mov_b32_e32 v18, 0
	v_mov_b32_e32 v19, 0
	v_mov_b32_e32 v20, 0
	v_mov_b32_e32 v21, 0
	v_mov_b32_e32 v22, 0
	v_mov_b32_e32 v23, 0
	v_mov_b32_e32 v24, 0
	v_mov_b32_e32 v25, 0
	v_mov_b32_e32 v26, 0
	v_mov_b32_e32 v27, 0
	v_mov_b32_e32 v28, 0
	v_mov_b32_e32 v29, 0
	v_mov_b32_e32 v30, 0
	v_mov_b32_e32 v31, 0
	v_mov_b32_e32 v32, 0
	v_mov_b32_e32 v33, 0
	v_mov_b32_e32 v34, 0
	v_mov_b32_e32 v35, 0
	v_mov_b32_e32 v36, 0
	v_mov_b32_e32 v37, 0
	v_mov_b32_e32 v38, 0
	v_mov_b32_e32 v39, 0
	v_mov_b32_e32 v40, 0
	v_mov_b32_e32 v41, 0
	v_mov_b32_e32 v42, 0
	v_mov_b32_e32 v43, 0
	v_mov_b32_e32 v44, 0
	v_mov_b32_e32 v45, 0
	v_mov_b32_e32 v46, 0
	v_mov_b32_e32 v47, 0
	v_mov_b32_e32 v48, 0
	v_mov_b32_e32 v49, 0
	v_mov_b32_e32 v50, 0
	v_mov_b32_e32 v51, 0
	v_mov_b32_e32 v52, 0
	v_mov_b32_e32 v53, 0
	v_mov_b32_e32 v54, 0
	v_mov_b32_e32 v55, 0
	v_mov_b32_e32 v56, 0
	v_mov_b32_e32 v57, 0
	v_mov_b32_e32 v58, 0
	v_mov_b32_e32 v59, 0
	v_mov_b32_e32 v60, 0
	v_mov_b32_e32 v61, 0
	v_mov_b32_e32 v62, 0
	v_mov_b32_e32 v63, 0
	v_mov_b32_e32 v64, 0
	v_mov_b32_e32 v65, 0
	v_mov_b32_e32 v66, 0
	v_mov_b32_e32 v67, 0
	v_mov_b32_e32 v68, 0
	v_mov_b32_e32 v69, 0
	v_mov_b32_e32 v70, 0
	v_mov_b32_e32 v71, 0
	v_mov_b32_e32 v72, 0
	v_mov_b32_e32 v73, 0
	v_mov_b32_e32 v74, 0
	v_mov_b32_e32 v75, 0
	v_mov_b32_e32 v76, 0
	v_mov_b32_e32 v77, 0
	v_mov_b32_e32 v78, 0
	v_mov_b32_e32 v79, 0
	v_mov_b32_e32 v80, 0
	v_mov_b32_e32 v81, 0
	s_mov_b32 s39, 0
.Lq1_kloop:
	s_cmp_eq_u32 s39, 0
	s_cbranch_scc1 .Lq1_w1a
	s_waitcnt vmcnt(0)
	s_branch .Lq1_w1b
.Lq1_w1a:
	s_waitcnt vmcnt(16)
.Lq1_w1b:
	s_barrier
	s_setprio 2
	s_cmp_eq_u32 s13, 1
	s_cbranch_scc0 .Lq1_x2
	ds_read_b128 v[196:199], v127
	ds_read_b128 v[200:203], v128
.Lq1_x2:
	s_add_i32 m0, s38, 0x8800
	ds_read_b128 v[82:85], v119
	global_load_lds_dwordx4 v114, s[4:5]
	ds_read_b128 v[86:89], v119 offset:2048
	s_add_i32 m0, s38, 0xc800
	ds_read_b128 v[90:93], v119 offset:4096
	global_load_lds_dwordx4 v114, s[6:7]
	ds_read_b128 v[94:97], v119 offset:6144
	s_add_i32 m0, s38, 0x9800
	ds_read_b128 v[164:167], v121
	global_load_lds_dwordx4 v115, s[4:5]
	ds_read_b128 v[168:171], v121 offset:2048
	s_add_i32 m0, s38, 0xd800
	ds_read_b128 v[172:175], v121 offset:4096
	global_load_lds_dwordx4 v115, s[6:7]
	ds_read_b128 v[176:179], v121 offset:6144
	s_add_i32 m0, s38, 0xa800
	ds_read_b128 v[98:101], v120
	global_load_lds_dwordx4 v116, s[4:5]
	ds_read_b128 v[102:105], v120 offset:2048
	s_add_i32 m0, s38, 0xe800
	ds_read_b128 v[106:109], v120 offset:4096
	global_load_lds_dwordx4 v116, s[6:7]
	ds_read_b128 v[110:113], v120 offset:6144
	s_add_i32 m0, s38, 0xb800
	ds_read_b128 v[180:183], v126
	global_load_lds_dwordx4 v117, s[4:5]
	ds_read_b128 v[184:187], v126 offset:2048
	s_add_i32 m0, s38, 0xf800
	ds_read_b128 v[188:191], v126 offset:4096
	global_load_lds_dwordx4 v117, s[6:7]
	ds_read_b128 v[192:195], v126 offset:6144
	s_cmp_eq_u32 s13, 1
	s_cbranch_scc0 .Lq1_nx3
	s_cmpk_lt_u32 s38, 0x800
	s_cbranch_scc0 .Lq1_nx3
	s_add_i32 m0, s38, 0x10800
	s_nop 0
	global_load_lds_dwordx4 v118, s[6:7]
.Lq1_nx3:
	s_add_u32 s4, s4, 0x80
	s_addc_u32 s5, s5, 0
	s_add_u32 s6, s6, 0x80
	s_addc_u32 s7, s7, 0
	s_setprio 0
	s_waitcnt lgkmcnt(8)
	v_mfma_f32_16x16x32_bf16 v[2:5], v[164:167], v[82:85], v[2:5]
	v_mfma_f32_16x16x32_bf16 v[6:9], v[168:171], v[82:85], v[6:9]
	v_mfma_f32_16x16x32_bf16 v[10:13], v[172:175], v[82:85], v[10:13]
	v_mfma_f32_16x16x32_bf16 v[14:17], v[176:179], v[82:85], v[14:17]
	v_mfma_f32_16x16x32_bf16 v[18:21], v[164:167], v[86:89], v[18:21]
	v_mfma_f32_16x16x32_bf16 v[22:25], v[168:171], v[86:89], v[22:25]
	v_mfma_f32_16x16x32_bf16 v[26:29], v[172:175], v[86:89], v[26:29]
	v_mfma_f32_16x16x32_bf16 v[30:33], v[176:179], v[86:89], v[30:33]
	v_mfma_f32_16x16x32_bf16 v[34:37], v[164:167], v[90:93], v[34:37]
	v_mfma_f32_16x16x32_bf16 v[38:41], v[168:171], v[90:93], v[38:41]
	v_mfma_f32_16x16x32_bf16 v[42:45], v[172:175], v[90:93], v[42:45]
	v_mfma_f32_16x16x32_bf16 v[46:49], v[176:179], v[90:93], v[46:49]
	v_mfma_f32_16x16x32_bf16 v[50:53], v[164:167], v[94:97], v[50:53]
	v_mfma_f32_16x16x32_bf16 v[54:57], v[168:171], v[94:97], v[54:57]
	v_mfma_f32_16x16x32_bf16 v[58:61], v[172:175], v[94:97], v[58:61]
	v_mfma_f32_16x16x32_bf16 v[62:65], v[176:179], v[94:97], v[62:65]
	s_waitcnt lgkmcnt(0)
	v_mfma_f32_16x16x32_bf16 v[2:5], v[180:183], v[98:101], v[2:5]
	v_mfma_f32_16x16x32_bf16 v[6:9], v[184:187], v[98:101], v[6:9]
	v_mfma_f32_16x16x32_bf16 v[10:13], v[188:191], v[98:101], v[10:13]
	v_mfma_f32_16x16x32_bf16 v[14:17], v[192:195], v[98:101], v[14:17]
	v_mfma_f32_16x16x32_bf16 v[18:21], v[180:183], v[102:105], v[18:21]
	v_mfma_f32_16x16x32_bf16 v[22:25], v[184:187], v[102:105], v[22:25]
	v_mfma_f32_16x16x32_bf16 v[26:29], v[188:191], v[102:105], v[26:29]
	v_mfma_f32_16x16x32_bf16 v[30:33], v[192:195], v[102:105], v[30:33]
	v_mfma_f32_16x16x32_bf16 v[34:37], v[180:183], v[106:109], v[34:37]
	v_mfma_f32_16x16x32_bf16 v[38:41], v[184:187], v[106:109], v[38:41]
	v_mfma_f32_16x16x32_bf16 v[42:45], v[188:191], v[106:109], v[42:45]
	v_mfma_f32_16x16x32_bf16 v[46:49], v[192:195], v[106:109], v[46:49]
	v_mfma_f32_16x16x32_bf16 v[50:53], v[180:183], v[110:113], v[50:53]
	v_mfma_f32_16x16x32_bf16 v[54:57], v[184:187], v[110:113], v[54:57]
	v_mfma_f32_16x16x32_bf16 v[58:61], v[188:191], v[110:113], v[58:61]
	v_mfma_f32_16x16x32_bf16 v[62:65], v[192:195], v[110:113], v[62:65]
	s_cmp_eq_u32 s13, 1
	s_cbranch_scc0 .Lq1_y4
	v_mfma_f32_16x16x32_bf16 v[66:69], v[196:199], v[82:85], v[66:69]
	v_mfma_f32_16x16x32_bf16 v[70:73], v[196:199], v[86:89], v[70:73]
	v_mfma_f32_16x16x32_bf16 v[74:77], v[196:199], v[90:93], v[74:77]
	v_mfma_f32_16x16x32_bf16 v[78:81], v[196:199], v[94:97], v[78:81]
	v_mfma_f32_16x16x32_bf16 v[66:69], v[200:203], v[98:101], v[66:69]
	v_mfma_f32_16x16x32_bf16 v[70:73], v[200:203], v[102:105], v[70:73]
	v_mfma_f32_16x16x32_bf16 v[74:77], v[200:203], v[106:109], v[74:77]
	v_mfma_f32_16x16x32_bf16 v[78:81], v[200:203], v[110:113], v[78:81]
.Lq1_y4:
	s_waitcnt vmcnt(0)
	s_barrier
	s_setprio 2
	s_cmp_eq_u32 s13, 1
	s_cbranch_scc0 .Lq1_x5
	ds_read_b128 v[196:199], v127 offset:34816
	ds_read_b128 v[200:203], v128 offset:34816
.Lq1_x5:
	s_cmpk_eq_u32 s39, 7
	s_cbranch_scc1 .Lq1_nopf
	s_add_i32 m0, s38, 0x0
	ds_read_b128 v[82:85], v119 offset:34816
	global_load_lds_dwordx4 v114, s[4:5]
	ds_read_b128 v[86:89], v119 offset:36864
	s_add_i32 m0, s38, 0x4000
	ds_read_b128 v[90:93], v119 offset:38912
	global_load_lds_dwordx4 v114, s[6:7]
	ds_read_b128 v[94:97], v119 offset:40960
	s_add_i32 m0, s38, 0x1000
	ds_read_b128 v[164:167], v121 offset:34816
	global_load_lds_dwordx4 v115, s[4:5]
	ds_read_b128 v[168:171], v121 offset:36864
	s_add_i32 m0, s38, 0x5000
	ds_read_b128 v[172:175], v121 offset:38912
	global_load_lds_dwordx4 v115, s[6:7]
	ds_read_b128 v[176:179], v121 offset:40960
	s_add_i32 m0, s38, 0x2000
	ds_read_b128 v[98:101], v120 offset:34816
	global_load_lds_dwordx4 v116, s[4:5]
	ds_read_b128 v[102:105], v120 offset:36864
	s_add_i32 m0, s38, 0x6000
	ds_read_b128 v[106:109], v120 offset:38912
	global_load_lds_dwordx4 v116, s[6:7]
	ds_read_b128 v[110:113], v120 offset:40960
	s_add_i32 m0, s38, 0x3000
	ds_read_b128 v[180:183], v126 offset:34816
	global_load_lds_dwordx4 v117, s[4:5]
	ds_read_b128 v[184:187], v126 offset:36864
	s_add_i32 m0, s38, 0x7000
	ds_read_b128 v[188:191], v126 offset:38912
	global_load_lds_dwordx4 v117, s[6:7]
	ds_read_b128 v[192:195], v126 offset:40960
	s_cmp_eq_u32 s13, 1
	s_cbranch_scc0 .Lq1_nx6
	s_cmpk_lt_u32 s38, 0x800
	s_cbranch_scc0 .Lq1_nx6
	s_add_i32 m0, s38, 0x8000
	s_nop 0
	global_load_lds_dwordx4 v118, s[6:7]
.Lq1_nx6:
	s_add_u32 s4, s4, 0x80
	s_addc_u32 s5, s5, 0
	s_add_u32 s6, s6, 0x80
	s_addc_u32 s7, s7, 0
	s_branch .Lq1_join
.Lq1_nopf:
	ds_read_b128 v[82:85], v119 offset:34816
	ds_read_b128 v[86:89], v119 offset:36864
	ds_read_b128 v[90:93], v119 offset:38912
	ds_read_b128 v[94:97], v119 offset:40960
	ds_read_b128 v[164:167], v121 offset:34816
	ds_read_b128 v[168:171], v121 offset:36864
	ds_read_b128 v[172:175], v121 offset:38912
	ds_read_b128 v[176:179], v121 offset:40960
	ds_read_b128 v[98:101], v120 offset:34816
	ds_read_b128 v[102:105], v120 offset:36864
	ds_read_b128 v[106:109], v120 offset:38912
	ds_read_b128 v[110:113], v120 offset:40960
	ds_read_b128 v[180:183], v126 offset:34816
	ds_read_b128 v[184:187], v126 offset:36864
	ds_read_b128 v[188:191], v126 offset:38912
	ds_read_b128 v[192:195], v126 offset:40960
.Lq1_join:
	s_setprio 0
	s_waitcnt lgkmcnt(8)
	v_mfma_f32_16x16x32_bf16 v[2:5], v[164:167], v[82:85], v[2:5]
	v_mfma_f32_16x16x32_bf16 v[6:9], v[168:171], v[82:85], v[6:9]
	v_mfma_f32_16x16x32_bf16 v[10:13], v[172:175], v[82:85], v[10:13]
	v_mfma_f32_16x16x32_bf16 v[14:17], v[176:179], v[82:85], v[14:17]
	v_mfma_f32_16x16x32_bf16 v[18:21], v[164:167], v[86:89], v[18:21]
	v_mfma_f32_16x16x32_bf16 v[22:25], v[168:171], v[86:89], v[22:25]
	v_mfma_f32_16x16x32_bf16 v[26:29], v[172:175], v[86:89], v[26:29]
	v_mfma_f32_16x16x32_bf16 v[30:33], v[176:179], v[86:89], v[30:33]
	v_mfma_f32_16x16x32_bf16 v[34:37], v[164:167], v[90:93], v[34:37]
	v_mfma_f32_16x16x32_bf16 v[38:41], v[168:171], v[90:93], v[38:41]
	v_mfma_f32_16x16x32_bf16 v[42:45], v[172:175], v[90:93], v[42:45]
	v_mfma_f32_16x16x32_bf16 v[46:49], v[176:179], v[90:93], v[46:49]
	v_mfma_f32_16x16x32_bf16 v[50:53], v[164:167], v[94:97], v[50:53]
	v_mfma_f32_16x16x32_bf16 v[54:57], v[168:171], v[94:97], v[54:57]
	v_mfma_f32_16x16x32_bf16 v[58:61], v[172:175], v[94:97], v[58:61]
	v_mfma_f32_16x16x32_bf16 v[62:65], v[176:179], v[94:97], v[62:65]
	s_waitcnt lgkmcnt(0)
	v_mfma_f32_16x16x32_bf16 v[2:5], v[180:183], v[98:101], v[2:5]
	v_mfma_f32_16x16x32_bf16 v[6:9], v[184:187], v[98:101], v[6:9]
	v_mfma_f32_16x16x32_bf16 v[10:13], v[188:191], v[98:101], v[10:13]
	v_mfma_f32_16x16x32_bf16 v[14:17], v[192:195], v[98:101], v[14:17]
	v_mfma_f32_16x16x32_bf16 v[18:21], v[180:183], v[102:105], v[18:21]
	v_mfma_f32_16x16x32_bf16 v[22:25], v[184:187], v[102:105], v[22:25]
	v_mfma_f32_16x16x32_bf16 v[26:29], v[188:191], v[102:105], v[26:29]
	v_mfma_f32_16x16x32_bf16 v[30:33], v[192:195], v[102:105], v[30:33]
	v_mfma_f32_16x16x32_bf16 v[34:37], v[180:183], v[106:109], v[34:37]
	v_mfma_f32_16x16x32_bf16 v[38:41], v[184:187], v[106:109], v[38:41]
	v_mfma_f32_16x16x32_bf16 v[42:45], v[188:191], v[106:109], v[42:45]
	v_mfma_f32_16x16x32_bf16 v[46:49], v[192:195], v[106:109], v[46:49]
	v_mfma_f32_16x16x32_bf16 v[50:53], v[180:183], v[110:113], v[50:53]
	v_mfma_f32_16x16x32_bf16 v[54:57], v[184:187], v[110:113], v[54:57]
	v_mfma_f32_16x16x32_bf16 v[58:61], v[188:191], v[110:113], v[58:61]
	v_mfma_f32_16x16x32_bf16 v[62:65], v[192:195], v[110:113], v[62:65]
	s_cmp_eq_u32 s13, 1
	s_cbranch_scc0 .Lq1_y7
	v_mfma_f32_16x16x32_bf16 v[66:69], v[196:199], v[82:85], v[66:69]
	v_mfma_f32_16x16x32_bf16 v[70:73], v[196:199], v[86:89], v[70:73]
	v_mfma_f32_16x16x32_bf16 v[74:77], v[196:199], v[90:93], v[74:77]
	v_mfma_f32_16x16x32_bf16 v[78:81], v[196:199], v[94:97], v[78:81]
	v_mfma_f32_16x16x32_bf16 v[66:69], v[200:203], v[98:101], v[66:69]
	v_mfma_f32_16x16x32_bf16 v[70:73], v[200:203], v[102:105], v[70:73]
	v_mfma_f32_16x16x32_bf16 v[74:77], v[200:203], v[106:109], v[74:77]
	v_mfma_f32_16x16x32_bf16 v[78:81], v[200:203], v[110:113], v[78:81]
.Lq1_y7:
	s_add_u32 s39, s39, 1
	s_cmpk_lt_u32 s39, 8
	s_cbranch_scc1 .Lq1_kloop
	s_add_u32 s47, s0, s96
	s_cmpk_ge_u32 s47, 0xff0
	s_cbranch_scc1 .Lq1_nonext
	s_mul_hi_u32 s1, s47, 0x88888889
	s_lshr_b32 s1, s1, 4
	s_mul_i32 s2, s1, 30
	s_sub_u32 s2, s47, s2
	s_cmp_eq_u32 s2, 29
	s_cselect_b32 s14, 1, 0
	s_lshl_b32 s15, s1, 18
	s_add_u32 s15, s15, 0x1a40000
	s_add_u32 s4, s26, s15
	s_addc_u32 s5, s27, 0
	s_lshl_b32 s15, s2, 18
	s_add_u32 s6, s26, s15
	s_addc_u32 s7, s27, 0
	s_add_i32 m0, s38, 0x0
	s_nop 0
	global_load_lds_dwordx4 v114, s[4:5]
	s_add_i32 m0, s38, 0x4000
	s_nop 0
	global_load_lds_dwordx4 v114, s[6:7]
	s_add_i32 m0, s38, 0x1000
	s_nop 0
	global_load_lds_dwordx4 v115, s[4:5]
	s_add_i32 m0, s38, 0x5000
	s_nop 0
	global_load_lds_dwordx4 v115, s[6:7]
	s_add_i32 m0, s38, 0x2000
	s_nop 0
	global_load_lds_dwordx4 v116, s[4:5]
	s_add_i32 m0, s38, 0x6000
	s_nop 0
	global_load_lds_dwordx4 v116, s[6:7]
	s_add_i32 m0, s38, 0x3000
	s_nop 0
	global_load_lds_dwordx4 v117, s[4:5]
	s_add_i32 m0, s38, 0x7000
	s_nop 0
	global_load_lds_dwordx4 v117, s[6:7]
	s_cmp_eq_u32 s14, 1
	s_cbranch_scc0 .Lq1_nx8
	s_cmpk_lt_u32 s38, 0x800
	s_cbranch_scc0 .Lq1_nx8
	s_add_i32 m0, s38, 0x8000
	s_nop 0
	global_load_lds_dwordx4 v118, s[6:7]
.Lq1_nx8:
	s_add_u32 s4, s4, 0x80
	s_addc_u32 s5, s5, 0
	s_add_u32 s6, s6, 0x80
	s_addc_u32 s7, s7, 0
.Lq1_nonext:
	s_nop 7
	s_nop 7
	v_cvt_pk_bf16_f32 v204, v2, v3
	v_cvt_pk_bf16_f32 v205, v4, v5
	v_cvt_pk_bf16_f32 v206, v6, v7
	v_cvt_pk_bf16_f32 v207, v8, v9
	s_nop 1
	v_permlane16_swap_b32_e32 v204, v206
	v_permlane16_swap_b32_e32 v205, v207
	s_nop 1
	global_store_dwordx4 v209, v[204:207], s[8:9]
	s_nop 1
	v_cvt_pk_bf16_f32 v204, v10, v11
	v_cvt_pk_bf16_f32 v205, v12, v13
	v_cvt_pk_bf16_f32 v206, v14, v15
	v_cvt_pk_bf16_f32 v207, v16, v17
	s_nop 1
	v_permlane16_swap_b32_e32 v204, v206
	v_permlane16_swap_b32_e32 v205, v207
	s_nop 1
	global_store_dwordx4 v209, v[204:207], s[8:9] offset:64
	s_nop 1
	v_cvt_pk_bf16_f32 v204, v18, v19
	v_cvt_pk_bf16_f32 v205, v20, v21
	v_cvt_pk_bf16_f32 v206, v22, v23
	v_cvt_pk_bf16_f32 v207, v24, v25
	s_nop 1
	v_permlane16_swap_b32_e32 v204, v206
	v_permlane16_swap_b32_e32 v205, v207
	s_nop 1
	global_store_dwordx4 v210, v[204:207], s[8:9]
	s_nop 1
	v_cvt_pk_bf16_f32 v204, v26, v27
	v_cvt_pk_bf16_f32 v205, v28, v29
	v_cvt_pk_bf16_f32 v206, v30, v31
	v_cvt_pk_bf16_f32 v207, v32, v33
	s_nop 1
	v_permlane16_swap_b32_e32 v204, v206
	v_permlane16_swap_b32_e32 v205, v207
	s_nop 1
	global_store_dwordx4 v210, v[204:207], s[8:9] offset:64
	s_nop 1
	v_cvt_pk_bf16_f32 v204, v34, v35
	v_cvt_pk_bf16_f32 v205, v36, v37
	v_cvt_pk_bf16_f32 v206, v38, v39
	v_cvt_pk_bf16_f32 v207, v40, v41
	s_nop 1
	v_permlane16_swap_b32_e32 v204, v206
	v_permlane16_swap_b32_e32 v205, v207
	s_nop 1
	global_store_dwordx4 v211, v[204:207], s[8:9]
	s_nop 1
	v_cvt_pk_bf16_f32 v204, v42, v43
	v_cvt_pk_bf16_f32 v205, v44, v45
	v_cvt_pk_bf16_f32 v206, v46, v47
	v_cvt_pk_bf16_f32 v207, v48, v49
	s_nop 1
	v_permlane16_swap_b32_e32 v204, v206
	v_permlane16_swap_b32_e32 v205, v207
	s_nop 1
	global_store_dwordx4 v211, v[204:207], s[8:9] offset:64
	s_nop 1
	v_cvt_pk_bf16_f32 v204, v50, v51
	v_cvt_pk_bf16_f32 v205, v52, v53
	v_cvt_pk_bf16_f32 v206, v54, v55
	v_cvt_pk_bf16_f32 v207, v56, v57
	s_nop 1
	v_permlane16_swap_b32_e32 v204, v206
	v_permlane16_swap_b32_e32 v205, v207
	s_nop 1
	global_store_dwordx4 v212, v[204:207], s[8:9]
	s_nop 1
	v_cvt_pk_bf16_f32 v204, v58, v59
	v_cvt_pk_bf16_f32 v205, v60, v61
	v_cvt_pk_bf16_f32 v206, v62, v63
	v_cvt_pk_bf16_f32 v207, v64, v65
	s_nop 1
	v_permlane16_swap_b32_e32 v204, v206
	v_permlane16_swap_b32_e32 v205, v207
	s_nop 1
	global_store_dwordx4 v212, v[204:207], s[8:9] offset:64
	s_nop 1
	s_cmp_eq_u32 s12, 22
	s_cbranch_scc0 .Lq1_ng
	s_cmp_eq_u32 s44, 0
	s_cbranch_scc0 .Lq1_ng
	s_mov_b64 s[98:99], exec
	s_mov_b64 exec, s[40:41]
	global_store_dwordx4 v133, v[2:5], s[10:11]
	global_store_dwordx4 v134, v[18:21], s[10:11]
	global_store_dwordx4 v135, v[34:37], s[10:11]
	global_store_dwordx4 v136, v[50:53], s[10:11]
	s_mov_b64 exec, s[98:99]
.Lq1_ng:
	s_cmp_eq_u32 s13, 1
	s_cbranch_scc0 .Lq1_nw
	s_cmp_eq_u32 s44, 1
	s_cbranch_scc0 .Lq1_nw
	v_cvt_pk_bf16_f32 v206, v66, v67
	v_cvt_pk_bf16_f32 v207, v68, v69
	global_store_dwordx2 v129, v[206:207], s[8:9] offset:128
	s_nop 1
	v_cvt_pk_bf16_f32 v206, v70, v71
	v_cvt_pk_bf16_f32 v207, v72, v73
	global_store_dwordx2 v130, v[206:207], s[8:9] offset:128
	s_nop 1
	v_cvt_pk_bf16_f32 v206, v74, v75
	v_cvt_pk_bf16_f32 v207, v76, v77
	global_store_dwordx2 v131, v[206:207], s[8:9] offset:128
	s_nop 1
	v_cvt_pk_bf16_f32 v206, v78, v79
	v_cvt_pk_bf16_f32 v207, v80, v81
	global_store_dwordx2 v132, v[206:207], s[8:9] offset:128
	s_nop 1
	s_mov_b64 s[98:99], exec
	s_mov_b64 exec, s[42:43]
	global_store_dwordx4 v133, v[66:69], s[10:11]
	global_store_dwordx4 v134, v[70:73], s[10:11]
	global_store_dwordx4 v135, v[74:77], s[10:11]
	global_store_dwordx4 v136, v[78:81], s[10:11]
	s_mov_b64 exec, s[98:99]
.Lq1_nw:
	s_mov_b32 s0, s47
	s_cmpk_lt_u32 s0, 0xff0
	s_cbranch_scc1 .Lq1_task
.Lq1_done:
	s_branch .LBB0_708
